# heavy diff loop: ALiBi bias on f32 VALU (fma with |q-k|) instead of the extra bf16 MFMA k-step; 2 fewer MFMAs per step
# speedup vs baseline: 1.0011x; 1.0011x over previous
.LBB0_301:
	s_add_i32 s81, s70, s74
	s_add_i32 s82, s81, -2
	s_add_i32 s4, s81, -4
	s_cmp_lt_i32 s4, s68
	s_cselect_b32 s4, s4, s82
	s_add_i32 s5, s81, -3
	s_add_i32 s8, s81, -1
	s_cmp_lt_i32 s5, s68
	s_cselect_b32 s80, s5, s8
	v_lshl_add_u32 v96, s80, 13, v185
	s_mov_b32 s5, m0
	s_mov_b32 m0, s76
	s_nop 0
	global_load_lds_dwordx4 v96, s[22:23]
	s_mov_b32 m0, s5
	v_exp_f32_e32 v80, v80
	s_mov_b32 s5, m0
	s_mov_b32 m0, s77
	s_nop 0
	global_load_lds_dwordx4 v96, s[24:25]
	s_mov_b32 m0, s5
	s_lshl_b32 s5, s4, 14
	v_add_u32_e32 v96, s5, v170
	s_mov_b32 s8, m0
	s_mov_b32 m0, s71
	s_nop 0
	global_load_lds_dwordx4 v96, s[6:7]
	s_mov_b32 m0, s8
	v_add_u32_e32 v96, s5, v169
	s_mov_b32 s5, m0
	s_mov_b32 m0, s72
	s_nop 0
	global_load_lds_dwordx4 v96, s[6:7]
	s_mov_b32 m0, s5
	ds_read_b128 v[200:203], v171
	ds_read_b128 v[204:207], v171 offset:4096
	ds_read_b128 v[208:211], v174
	ds_read_b128 v[212:215], v174 offset:4096
	s_lshl_b32 s5, s4, 6
	v_or_b32_e32 v240, s5, v158
	v_sub_u32_e32 v240, v159, v240
	v_cvt_f32_i32_e32 v242, v240
	v_exp_f32_e32 v81, v81
	s_nop 0
	v_exp_f32_e32 v82, v82
	v_exp_f32_e32 v83, v83
	s_waitcnt lgkmcnt(3)
	v_mfma_f32_32x32x16_bf16 v[112:127], v[200:203], v[144:147], 0
	ds_read_b128 v[216:219], v172
	ds_read_b128 v[220:223], v172 offset:4096
	ds_read_b128 v[224:227], v173
	ds_read_b128 v[228:231], v173 offset:4096
	v_exp_f32_e32 v84, v84
	v_exp_f32_e32 v85, v85
	s_waitcnt lgkmcnt(6)
	v_mfma_f32_32x32x16_bf16 v[96:111], v[204:207], v[144:147], 0
	v_exp_f32_e32 v86, v86
	v_exp_f32_e32 v87, v87
	v_cvt_pk_bf16_f32 v200, v80, v81
	v_cvt_pk_bf16_f32 v201, v82, v83
	v_cvt_pk_bf16_f32 v202, v84, v85
	v_cvt_pk_bf16_f32 v203, v86, v87
	s_waitcnt lgkmcnt(5)
	v_mfma_f32_32x32x16_bf16 v[112:127], v[208:211], v[140:143], v[112:127]
	v_exp_f32_e32 v88, v88
	v_exp_f32_e32 v89, v89
	s_waitcnt lgkmcnt(4)
	v_mfma_f32_32x32x16_bf16 v[96:111], v[212:215], v[140:143], v[96:111]
	v_exp_f32_e32 v90, v90
	v_exp_f32_e32 v91, v91
	ds_read_b64_tr_b16 v[204:205], v175 offset:49152
	ds_read_b64_tr_b16 v[206:207], v176 offset:49152
	ds_read_b64_tr_b16 v[208:209], v177 offset:49152
	ds_read_b64_tr_b16 v[210:211], v178 offset:49152
	ds_read_b64_tr_b16 v[212:213], v179 offset:49152
	ds_read_b64_tr_b16 v[214:215], v182 offset:49152
	ds_read_b64_tr_b16 v[232:233], v183 offset:49152
	ds_read_b64_tr_b16 v[234:235], v184 offset:49152
	s_waitcnt lgkmcnt(11)
	v_mfma_f32_32x32x16_bf16 v[112:127], v[216:219], v[136:139], v[112:127]
	v_exp_f32_e32 v92, v92
	v_exp_f32_e32 v93, v93
	s_waitcnt lgkmcnt(10)
	v_mfma_f32_32x32x16_bf16 v[96:111], v[220:223], v[136:139], v[96:111]
	v_exp_f32_e32 v94, v94
	v_exp_f32_e32 v95, v95
	v_cvt_pk_bf16_f32 v216, v88, v89
	v_cvt_pk_bf16_f32 v217, v90, v91
	v_cvt_pk_bf16_f32 v218, v92, v93
	v_cvt_pk_bf16_f32 v219, v94, v95
	s_waitcnt lgkmcnt(9)
	v_mfma_f32_32x32x16_bf16 v[112:127], v[224:227], v[132:135], v[112:127]
	s_waitcnt lgkmcnt(8)
	v_mfma_f32_32x32x16_bf16 v[96:111], v[228:231], v[132:135], v[96:111]
	ds_read_b64_tr_b16 v[220:221], v175 offset:53248
	ds_read_b64_tr_b16 v[222:223], v176 offset:53248
	ds_read_b64_tr_b16 v[224:225], v177 offset:53248
	ds_read_b64_tr_b16 v[226:227], v178 offset:53248
	ds_read_b64_tr_b16 v[228:229], v179 offset:53248
	ds_read_b64_tr_b16 v[230:231], v182 offset:53248
	ds_read_b64_tr_b16 v[236:237], v183 offset:53248
	ds_read_b64_tr_b16 v[238:239], v184 offset:53248
	s_waitcnt lgkmcnt(14)
	v_mfma_f32_32x32x16_bf16 v[48:63], v[204:207], v[200:203], v[48:63]
	v_exp_f32_e32 v64, v64
	v_exp_f32_e32 v65, v65
	s_waitcnt lgkmcnt(12)
	v_mfma_f32_32x32x16_bf16 v[32:47], v[208:211], v[200:203], v[32:47]
	v_exp_f32_e32 v66, v66
	v_exp_f32_e32 v67, v67
	s_waitcnt lgkmcnt(10)
	v_mfma_f32_32x32x16_bf16 v[16:31], v[212:215], v[200:203], v[16:31]
	v_exp_f32_e32 v68, v68
	v_exp_f32_e32 v69, v69
	s_waitcnt lgkmcnt(8)
	v_mfma_f32_32x32x16_bf16 v[0:15], v[232:235], v[200:203], v[0:15]
	v_exp_f32_e32 v70, v70
	v_exp_f32_e32 v71, v71
	v_cvt_pk_bf16_f32 v204, v64, v65
	v_cvt_pk_bf16_f32 v205, v66, v67
	v_cvt_pk_bf16_f32 v206, v68, v69
	v_cvt_pk_bf16_f32 v207, v70, v71
	ds_read_b64_tr_b16 v[200:201], v175 offset:57344
	ds_read_b64_tr_b16 v[202:203], v176 offset:57344
	ds_read_b64_tr_b16 v[208:209], v177 offset:57344
	ds_read_b64_tr_b16 v[210:211], v178 offset:57344
	ds_read_b64_tr_b16 v[212:213], v179 offset:57344
	ds_read_b64_tr_b16 v[214:215], v182 offset:57344
	ds_read_b64_tr_b16 v[232:233], v183 offset:57344
	ds_read_b64_tr_b16 v[234:235], v184 offset:57344
	s_waitcnt lgkmcnt(14)
	v_mfma_f32_32x32x16_bf16 v[48:63], v[220:223], v[216:219], v[48:63]
	v_mov_b32_e32 v241, v242
	v_subrev_f32_e32 v243, 1.0, v242
	v_subrev_f32_e32 v244, 2.0, v242
	v_fma_f32 v112, -v160, |v241|, v112
	v_fma_f32 v113, -v160, |v243|, v113
	v_fma_f32 v114, -v160, |v244|, v114
	v_exp_f32_e32 v72, v72
	s_waitcnt lgkmcnt(12)
	v_mfma_f32_32x32x16_bf16 v[32:47], v[224:227], v[216:219], v[32:47]
	v_subrev_f32_e32 v241, 0x40400000, v242
	v_subrev_f32_e32 v243, 4.0, v242
	v_subrev_f32_e32 v244, 0x40a00000, v242
	v_fma_f32 v115, -v160, |v241|, v115
	v_fma_f32 v116, -v160, |v243|, v116
	v_fma_f32 v117, -v160, |v244|, v117
	v_exp_f32_e32 v73, v73
	s_waitcnt lgkmcnt(10)
	v_mfma_f32_32x32x16_bf16 v[16:31], v[228:231], v[216:219], v[16:31]
	v_subrev_f32_e32 v241, 0x40c00000, v242
	v_subrev_f32_e32 v243, 0x40e00000, v242
	v_subrev_f32_e32 v244, 0x41800000, v242
	v_fma_f32 v118, -v160, |v241|, v118
	v_fma_f32 v119, -v160, |v243|, v119
	v_fma_f32 v120, -v160, |v244|, v120
	v_exp_f32_e32 v74, v74
	s_waitcnt lgkmcnt(8)
	v_mfma_f32_32x32x16_bf16 v[0:15], v[236:239], v[216:219], v[0:15]
	v_subrev_f32_e32 v241, 0x41880000, v242
	v_subrev_f32_e32 v243, 0x41900000, v242
	v_subrev_f32_e32 v244, 0x41980000, v242
	v_fma_f32 v121, -v160, |v241|, v121
	v_fma_f32 v122, -v160, |v243|, v122
	v_fma_f32 v123, -v160, |v244|, v123
	v_exp_f32_e32 v75, v75
	ds_read_b64_tr_b16 v[216:217], v175 offset:61440
	ds_read_b64_tr_b16 v[218:219], v176 offset:61440
	ds_read_b64_tr_b16 v[220:221], v177 offset:61440
	ds_read_b64_tr_b16 v[222:223], v178 offset:61440
	ds_read_b64_tr_b16 v[224:225], v179 offset:61440
	ds_read_b64_tr_b16 v[226:227], v182 offset:61440
	ds_read_b64_tr_b16 v[228:229], v183 offset:61440
	ds_read_b64_tr_b16 v[230:231], v184 offset:61440
	s_waitcnt lgkmcnt(14)
	v_mfma_f32_32x32x16_bf16 v[48:63], v[200:203], v[204:207], v[48:63]
	v_subrev_f32_e32 v241, 0x41a00000, v242
	v_subrev_f32_e32 v243, 0x41a80000, v242
	v_subrev_f32_e32 v244, 0x41b00000, v242
	v_fma_f32 v124, -v160, |v241|, v124
	v_fma_f32 v125, -v160, |v243|, v125
	v_fma_f32 v126, -v160, |v244|, v126
	v_exp_f32_e32 v76, v76
	s_waitcnt lgkmcnt(12)
	v_mfma_f32_32x32x16_bf16 v[32:47], v[208:211], v[204:207], v[32:47]
	v_subrev_f32_e32 v241, 0x41b80000, v242
	v_subrev_f32_e32 v243, 0x42000000, v242
	v_subrev_f32_e32 v244, 0x42040000, v242
	v_fma_f32 v127, -v160, |v241|, v127
	v_fma_f32 v96, -v160, |v243|, v96
	v_fma_f32 v97, -v160, |v244|, v97
	v_exp_f32_e32 v77, v77
	s_waitcnt lgkmcnt(10)
	v_mfma_f32_32x32x16_bf16 v[16:31], v[212:215], v[204:207], v[16:31]
	v_subrev_f32_e32 v241, 0x42080000, v242
	v_subrev_f32_e32 v243, 0x420c0000, v242
	v_subrev_f32_e32 v244, 0x42100000, v242
	v_fma_f32 v98, -v160, |v241|, v98
	v_fma_f32 v99, -v160, |v243|, v99
	v_fma_f32 v100, -v160, |v244|, v100
	v_exp_f32_e32 v78, v78
	s_waitcnt lgkmcnt(8)
	v_mfma_f32_32x32x16_bf16 v[0:15], v[232:235], v[204:207], v[0:15]
	v_subrev_f32_e32 v241, 0x42140000, v242
	v_subrev_f32_e32 v243, 0x42180000, v242
	v_subrev_f32_e32 v244, 0x421c0000, v242
	v_fma_f32 v101, -v160, |v241|, v101
	v_fma_f32 v102, -v160, |v243|, v102
	v_fma_f32 v103, -v160, |v244|, v103
	v_exp_f32_e32 v79, v79
	v_cvt_pk_bf16_f32 v200, v72, v73
	v_cvt_pk_bf16_f32 v201, v74, v75
	v_cvt_pk_bf16_f32 v202, v76, v77
	v_cvt_pk_bf16_f32 v203, v78, v79
	s_waitcnt lgkmcnt(6)
	s_nop 0
	v_mfma_f32_32x32x16_bf16 v[48:63], v[216:219], v[200:203], v[48:63]
	v_subrev_f32_e32 v241, 0x42400000, v242
	v_subrev_f32_e32 v243, 0x42440000, v242
	v_fma_f32 v104, -v160, |v241|, v104
	v_fma_f32 v105, -v160, |v243|, v105
	s_waitcnt lgkmcnt(4)
	v_mfma_f32_32x32x16_bf16 v[32:47], v[220:223], v[200:203], v[32:47]
	v_subrev_f32_e32 v241, 0x42480000, v242
	v_subrev_f32_e32 v243, 0x424c0000, v242
	v_fma_f32 v106, -v160, |v241|, v106
	v_fma_f32 v107, -v160, |v243|, v107
	s_waitcnt lgkmcnt(2)
	v_mfma_f32_32x32x16_bf16 v[16:31], v[224:227], v[200:203], v[16:31]
	v_subrev_f32_e32 v241, 0x42500000, v242
	v_subrev_f32_e32 v243, 0x42540000, v242
	v_fma_f32 v108, -v160, |v241|, v108
	v_fma_f32 v109, -v160, |v243|, v109
	s_waitcnt lgkmcnt(0)
	v_mfma_f32_32x32x16_bf16 v[0:15], v[228:231], v[200:203], v[0:15]
	v_subrev_f32_e32 v241, 0x42580000, v242
	v_subrev_f32_e32 v243, 0x425c0000, v242
	v_fma_f32 v110, -v160, |v241|, v110
	v_fma_f32 v111, -v160, |v243|, v111
	s_waitcnt vmcnt(0) lgkmcnt(0)
	s_barrier
	s_cmp_ge_i32 s74, s20
	s_cbranch_scc1 .LBB0_303
	s_cmp_lt_i32 s82, s68
	s_cselect_b32 s4, s82, s81
	v_lshl_add_u32 v128, s4, 13, v185
	s_mov_b32 s4, m0
	s_mov_b32 m0, s73
	s_nop 0
	global_load_lds_dwordx4 v128, s[22:23]
	s_mov_b32 m0, s4
	s_nop 0
	s_mov_b32 s4, m0
	s_mov_b32 m0, s75
	s_nop 0
	global_load_lds_dwordx4 v128, s[24:25]
	s_mov_b32 m0, s4
.LBB0_303:
	v_add_f32_e32 v80, 0, v80
	v_add_f32_e32 v80, v81, v80
	v_add_f32_e32 v80, v82, v80
	v_add_f32_e32 v80, v83, v80
	v_add_f32_e32 v80, v84, v80
	v_add_f32_e32 v80, v85, v80
	v_add_f32_e32 v80, v86, v80
	v_add_f32_e32 v80, v87, v80
	v_add_f32_e32 v80, v88, v80
	v_add_f32_e32 v80, v89, v80
	v_add_f32_e32 v80, v90, v80
	v_add_f32_e32 v80, v91, v80
	v_add_f32_e32 v80, v92, v80
	v_add_f32_e32 v80, v93, v80
	v_add_f32_e32 v80, v94, v80
	v_add_f32_e32 v80, v95, v80
	v_add_f32_e32 v64, v64, v80
	v_add_f32_e32 v64, v65, v64
	v_add_f32_e32 v64, v66, v64
	v_add_f32_e32 v64, v67, v64
	v_add_f32_e32 v64, v68, v64
	v_add_f32_e32 v64, v69, v64
	v_add_f32_e32 v64, v70, v64
	v_add_f32_e32 v64, v71, v64
	v_add_f32_e32 v64, v72, v64
	v_add_f32_e32 v64, v73, v64
	v_add_f32_e32 v64, v74, v64
	v_add_f32_e32 v64, v75, v64
	v_add_f32_e32 v64, v76, v64
	v_add_f32_e32 v64, v77, v64
	v_add_f32_e32 v64, v78, v64
	v_add_f32_e32 v64, v79, v64
	s_lshl_b32 s4, s80, 14
	v_add_f32_e32 v192, v188, v64
	v_add_u32_e32 v64, s4, v170
	s_mov_b32 s5, m0
	s_mov_b32 m0, s78
	s_nop 0
	global_load_lds_dwordx4 v64, s[6:7]
	s_mov_b32 m0, s5
	v_add_u32_e32 v64, s4, v169
	s_mov_b32 s4, m0
	s_mov_b32 m0, s79
	s_nop 0
	global_load_lds_dwordx4 v64, s[6:7]
	s_mov_b32 m0, s4
	ds_read_b128 v[188:191], v171 offset:32768
	ds_read_b128 v[200:203], v171 offset:36864
	ds_read_b128 v[204:207], v174 offset:32768
	ds_read_b128 v[208:211], v174 offset:36864
	s_lshl_b32 s4, s80, 6
	v_or_b32_e32 v240, s4, v158
	v_sub_u32_e32 v240, v159, v240
	v_cvt_f32_i32_e32 v242, v240
	v_exp_f32_e32 v224, v112
	v_exp_f32_e32 v225, v113
	v_add_f32_e32 v64, 0, v224
	v_add_f32_e32 v64, v225, v64
	v_exp_f32_e32 v226, v114
	v_exp_f32_e32 v227, v115
	v_add_f32_e32 v64, v226, v64
	v_add_f32_e32 v228, v227, v64
	s_waitcnt lgkmcnt(3)
	v_mfma_f32_32x32x16_bf16 v[80:95], v[188:191], v[144:147], 0
	ds_read_b128 v[112:115], v172 offset:32768
	ds_read_b128 v[212:215], v172 offset:36864
	ds_read_b128 v[216:219], v173 offset:32768
	ds_read_b128 v[220:223], v173 offset:36864
	v_exp_f32_e32 v128, v116
	v_exp_f32_e32 v129, v117
	v_add_f32_e32 v116, v128, v228
	v_add_f32_e32 v130, v129, v116
	s_waitcnt lgkmcnt(6)
	v_mfma_f32_32x32x16_bf16 v[64:79], v[200:203], v[144:147], 0
	v_exp_f32_e32 v188, v118
	v_exp_f32_e32 v119, v119
	v_cvt_pk_bf16_f32 v116, v224, v225
	v_cvt_pk_bf16_f32 v117, v226, v227
	v_add_f32_e32 v118, v188, v130
	v_add_f32_e32 v130, v119, v118
	v_cvt_pk_bf16_f32 v118, v128, v129
	v_cvt_pk_bf16_f32 v119, v188, v119
	s_waitcnt lgkmcnt(5)
	v_mfma_f32_32x32x16_bf16 v[80:95], v[204:207], v[140:143], v[80:95]
	v_exp_f32_e32 v128, v120
	v_exp_f32_e32 v129, v121
	v_add_f32_e32 v120, v128, v130
	v_add_f32_e32 v120, v129, v120
	s_waitcnt lgkmcnt(4)
	v_mfma_f32_32x32x16_bf16 v[64:79], v[208:211], v[140:143], v[64:79]
	v_exp_f32_e32 v130, v122
	v_exp_f32_e32 v224, v123
	v_add_f32_e32 v120, v130, v120
	v_add_f32_e32 v225, v224, v120
	ds_read_b64_tr_b16 v[120:121], v175 offset:16384
	ds_read_b64_tr_b16 v[122:123], v176 offset:16384
	ds_read_b64_tr_b16 v[188:189], v177 offset:16384
	ds_read_b64_tr_b16 v[190:191], v178 offset:16384
	ds_read_b64_tr_b16 v[200:201], v179 offset:16384
	ds_read_b64_tr_b16 v[202:203], v182 offset:16384
	ds_read_b64_tr_b16 v[204:205], v183 offset:16384
	ds_read_b64_tr_b16 v[206:207], v184 offset:16384
	s_waitcnt lgkmcnt(11)
	v_mfma_f32_32x32x16_bf16 v[80:95], v[112:115], v[136:139], v[80:95]
	v_exp_f32_e32 v124, v124
	v_exp_f32_e32 v125, v125
	v_add_f32_e32 v112, v124, v225
	v_add_f32_e32 v114, v125, v112
	s_waitcnt lgkmcnt(10)
	v_mfma_f32_32x32x16_bf16 v[64:79], v[212:215], v[136:139], v[64:79]
	v_exp_f32_e32 v115, v126
	v_exp_f32_e32 v126, v127
	v_cvt_pk_bf16_f32 v112, v128, v129
	v_cvt_pk_bf16_f32 v113, v130, v224
	v_add_f32_e32 v114, v115, v114
	v_add_f32_e32 v128, v126, v114
	v_cvt_pk_bf16_f32 v114, v124, v125
	v_cvt_pk_bf16_f32 v115, v115, v126
	s_waitcnt lgkmcnt(9)
	v_mfma_f32_32x32x16_bf16 v[80:95], v[216:219], v[132:135], v[80:95]
	s_waitcnt lgkmcnt(8)
	v_mfma_f32_32x32x16_bf16 v[64:79], v[220:223], v[132:135], v[64:79]
	ds_read_b64_tr_b16 v[124:125], v175 offset:20480
	ds_read_b64_tr_b16 v[126:127], v176 offset:20480
	ds_read_b64_tr_b16 v[208:209], v177 offset:20480
	ds_read_b64_tr_b16 v[210:211], v178 offset:20480
	ds_read_b64_tr_b16 v[212:213], v179 offset:20480
	ds_read_b64_tr_b16 v[214:215], v182 offset:20480
	ds_read_b64_tr_b16 v[216:217], v183 offset:20480
	ds_read_b64_tr_b16 v[218:219], v184 offset:20480
	s_waitcnt lgkmcnt(14)
	v_mfma_f32_32x32x16_bf16 v[48:63], v[120:123], v[116:119], v[48:63]
	v_exp_f32_e32 v96, v96
	v_exp_f32_e32 v97, v97
	v_add_f32_e32 v120, v96, v128
	v_add_f32_e32 v120, v97, v120
	s_waitcnt lgkmcnt(12)
	v_mfma_f32_32x32x16_bf16 v[32:47], v[188:191], v[116:119], v[32:47]
	v_exp_f32_e32 v98, v98
	v_exp_f32_e32 v99, v99
	v_add_f32_e32 v120, v98, v120
	v_add_f32_e32 v120, v99, v120
	s_waitcnt lgkmcnt(10)
	v_mfma_f32_32x32x16_bf16 v[16:31], v[200:203], v[116:119], v[16:31]
	v_exp_f32_e32 v100, v100
	v_exp_f32_e32 v101, v101
	v_add_f32_e32 v120, v100, v120
	v_add_f32_e32 v120, v101, v120
	s_waitcnt lgkmcnt(8)
	v_mfma_f32_32x32x16_bf16 v[0:15], v[204:207], v[116:119], v[0:15]
	v_exp_f32_e32 v102, v102
	v_exp_f32_e32 v103, v103
	v_cvt_pk_bf16_f32 v96, v96, v97
	v_cvt_pk_bf16_f32 v97, v98, v99
	v_add_f32_e32 v98, v102, v120
	v_add_f32_e32 v128, v103, v98
	v_cvt_pk_bf16_f32 v98, v100, v101
	v_cvt_pk_bf16_f32 v99, v102, v103
	ds_read_b64_tr_b16 v[100:101], v175 offset:24576
	ds_read_b64_tr_b16 v[102:103], v176 offset:24576
	ds_read_b64_tr_b16 v[116:117], v177 offset:24576
	ds_read_b64_tr_b16 v[118:119], v178 offset:24576
	ds_read_b64_tr_b16 v[120:121], v179 offset:24576
	ds_read_b64_tr_b16 v[122:123], v182 offset:24576
	ds_read_b64_tr_b16 v[188:189], v183 offset:24576
	ds_read_b64_tr_b16 v[190:191], v184 offset:24576
	s_waitcnt lgkmcnt(14)
	v_mfma_f32_32x32x16_bf16 v[48:63], v[124:127], v[112:115], v[48:63]
	v_mov_b32_e32 v241, v242
	v_subrev_f32_e32 v243, 1.0, v242
	v_subrev_f32_e32 v244, 2.0, v242
	v_fma_f32 v80, -v160, |v241|, v80
	v_fma_f32 v81, -v160, |v243|, v81
	v_fma_f32 v82, -v160, |v244|, v82
	v_exp_f32_e32 v129, v104
	s_nop 0
	v_add_f32_e32 v104, v129, v128
	s_waitcnt lgkmcnt(12)
	v_mfma_f32_32x32x16_bf16 v[32:47], v[208:211], v[112:115], v[32:47]
	v_subrev_f32_e32 v241, 0x40400000, v242
	v_subrev_f32_e32 v243, 4.0, v242
	v_subrev_f32_e32 v244, 0x40a00000, v242
	v_fma_f32 v83, -v160, |v241|, v83
	v_fma_f32 v84, -v160, |v243|, v84
	v_fma_f32 v85, -v160, |v244|, v85
	v_exp_f32_e32 v128, v105
	s_nop 0
	v_add_f32_e32 v104, v128, v104
	s_waitcnt lgkmcnt(10)
	v_mfma_f32_32x32x16_bf16 v[16:31], v[212:215], v[112:115], v[16:31]
	v_subrev_f32_e32 v241, 0x40c00000, v242
	v_subrev_f32_e32 v243, 0x40e00000, v242
	v_subrev_f32_e32 v244, 0x41800000, v242
	v_fma_f32 v86, -v160, |v241|, v86
	v_fma_f32 v87, -v160, |v243|, v87
	v_fma_f32 v88, -v160, |v244|, v88
	v_exp_f32_e32 v130, v106
	s_nop 0
	v_add_f32_e32 v104, v130, v104
	s_waitcnt lgkmcnt(8)
	v_mfma_f32_32x32x16_bf16 v[0:15], v[216:219], v[112:115], v[0:15]
	v_subrev_f32_e32 v241, 0x41880000, v242
	v_subrev_f32_e32 v243, 0x41900000, v242
	v_subrev_f32_e32 v244, 0x41980000, v242
	v_fma_f32 v89, -v160, |v241|, v89
	v_fma_f32 v90, -v160, |v243|, v90
	v_fma_f32 v91, -v160, |v244|, v91
	v_exp_f32_e32 v204, v107
	s_nop 0
	v_add_f32_e32 v205, v204, v104
	ds_read_b64_tr_b16 v[104:105], v175 offset:28672
	ds_read_b64_tr_b16 v[106:107], v176 offset:28672
	ds_read_b64_tr_b16 v[112:113], v177 offset:28672
	ds_read_b64_tr_b16 v[114:115], v178 offset:28672
	ds_read_b64_tr_b16 v[124:125], v179 offset:28672
	ds_read_b64_tr_b16 v[126:127], v182 offset:28672
	ds_read_b64_tr_b16 v[200:201], v183 offset:28672
	ds_read_b64_tr_b16 v[202:203], v184 offset:28672
	s_waitcnt lgkmcnt(14)
	v_mfma_f32_32x32x16_bf16 v[48:63], v[100:103], v[96:99], v[48:63]
	v_subrev_f32_e32 v241, 0x41a00000, v242
	v_subrev_f32_e32 v243, 0x41a80000, v242
	v_subrev_f32_e32 v244, 0x41b00000, v242
	v_fma_f32 v92, -v160, |v241|, v92
	v_fma_f32 v93, -v160, |v243|, v93
	v_fma_f32 v94, -v160, |v244|, v94
	v_exp_f32_e32 v108, v108
	s_nop 0
	v_add_f32_e32 v100, v108, v205
	s_waitcnt lgkmcnt(12)
	v_mfma_f32_32x32x16_bf16 v[32:47], v[116:119], v[96:99], v[32:47]
	v_subrev_f32_e32 v241, 0x41b80000, v242
	v_subrev_f32_e32 v243, 0x42000000, v242
	v_subrev_f32_e32 v244, 0x42040000, v242
	v_fma_f32 v95, -v160, |v241|, v95
	v_fma_f32 v64, -v160, |v243|, v64
	v_fma_f32 v65, -v160, |v244|, v65
	v_exp_f32_e32 v102, v109
	s_nop 0
	v_add_f32_e32 v100, v102, v100
	s_waitcnt lgkmcnt(10)
	v_mfma_f32_32x32x16_bf16 v[16:31], v[120:123], v[96:99], v[16:31]
	v_subrev_f32_e32 v241, 0x42080000, v242
	v_subrev_f32_e32 v243, 0x420c0000, v242
	v_subrev_f32_e32 v244, 0x42100000, v242
	v_fma_f32 v66, -v160, |v241|, v66
	v_fma_f32 v67, -v160, |v243|, v67
	v_fma_f32 v68, -v160, |v244|, v68
	v_exp_f32_e32 v103, v110
	s_nop 0
	v_add_f32_e32 v109, v103, v100
	s_waitcnt lgkmcnt(8)
	v_mfma_f32_32x32x16_bf16 v[0:15], v[188:191], v[96:99], v[0:15]
	v_subrev_f32_e32 v241, 0x42140000, v242
	v_subrev_f32_e32 v243, 0x42180000, v242
	v_subrev_f32_e32 v244, 0x421c0000, v242
	v_fma_f32 v69, -v160, |v241|, v69
	v_fma_f32 v70, -v160, |v243|, v70
	v_fma_f32 v71, -v160, |v244|, v71
	v_exp_f32_e32 v110, v111
	v_cvt_pk_bf16_f32 v100, v129, v128
	v_cvt_pk_bf16_f32 v101, v130, v204
	v_cvt_pk_bf16_f32 v102, v108, v102
	v_add_f32_e32 v108, v110, v109
	v_cvt_pk_bf16_f32 v103, v103, v110
	s_waitcnt lgkmcnt(6)
	s_nop 0
	v_mfma_f32_32x32x16_bf16 v[48:63], v[104:107], v[100:103], v[48:63]
	v_subrev_f32_e32 v241, 0x42400000, v242
	v_subrev_f32_e32 v243, 0x42440000, v242
	v_fma_f32 v72, -v160, |v241|, v72
	v_fma_f32 v73, -v160, |v243|, v73
	s_waitcnt lgkmcnt(4)
	v_mfma_f32_32x32x16_bf16 v[32:47], v[112:115], v[100:103], v[32:47]
	v_subrev_f32_e32 v241, 0x42480000, v242
	v_subrev_f32_e32 v243, 0x424c0000, v242
	v_fma_f32 v74, -v160, |v241|, v74
	v_fma_f32 v75, -v160, |v243|, v75
	s_waitcnt lgkmcnt(2)
	v_mfma_f32_32x32x16_bf16 v[16:31], v[124:127], v[100:103], v[16:31]
	v_subrev_f32_e32 v241, 0x42500000, v242
	v_subrev_f32_e32 v243, 0x42540000, v242
	v_fma_f32 v76, -v160, |v241|, v76
	v_fma_f32 v77, -v160, |v243|, v77
	s_waitcnt lgkmcnt(0)
	v_mfma_f32_32x32x16_bf16 v[0:15], v[200:203], v[100:103], v[0:15]
	v_subrev_f32_e32 v241, 0x42580000, v242
	v_subrev_f32_e32 v243, 0x425c0000, v242
	v_fma_f32 v78, -v160, |v241|, v78
	v_fma_f32 v79, -v160, |v243|, v79
	s_waitcnt vmcnt(0) lgkmcnt(0)
	s_barrier
	s_add_i32 s4, s74, 2
	s_add_i32 s5, s74, 1
	v_add_f32_e32 v188, v192, v108
	s_cmp_lt_i32 s5, s20
	s_cbranch_scc0 .LBB0_305
	s_mov_b32 s74, s4
	s_branch .LBB0_301
